# P6/P12: GEMM-output row loads without the nt hint (on top of P3/P4 non-nt loads)
# speedup vs baseline: 1.0066x; 1.0024x over previous
.LBB0_756:
	v_ashrrev_i32_e32 v73, 31, v72
	v_lshlrev_b64 v[86:87], 12, v[72:73]
	v_lshl_add_u64 v[32:33], v[74:75], 0, v[86:87]
	global_load_dwordx2 v[56:57], v[32:33], off
	global_load_dwordx2 v[58:59], v[32:33], off offset:512
	global_load_dwordx2 v[60:61], v[32:33], off offset:1024
	global_load_dwordx2 v[62:63], v[32:33], off offset:1536
	global_load_dwordx2 v[64:65], v[32:33], off offset:2560
	global_load_dwordx2 v[66:67], v[32:33], off offset:2048
	global_load_dwordx2 v[68:69], v[32:33], off offset:3584
	global_load_dwordx2 v[84:85], v[32:33], off offset:3072
	v_lshlrev_b64 v[88:89], 13, v[72:73]
	v_lshl_add_u64 v[32:33], v[80:81], 0, v[88:89]
	v_add_co_u32_e32 v94, vcc, s3, v32
	global_load_dwordx4 v[52:55], v[32:33], off nt
	global_load_dwordx4 v[48:51], v[32:33], off offset:1024 nt
	global_load_dwordx4 v[44:47], v[32:33], off offset:2048 nt
	global_load_dwordx4 v[40:43], v[32:33], off offset:3072 nt
	v_addc_co_u32_e32 v95, vcc, 0, v33, vcc
	global_load_dwordx4 v[36:39], v[94:95], off nt
	global_load_dwordx4 v[32:35], v[94:95], off offset:1024 nt
	global_load_dwordx4 v[90:93], v[94:95], off offset:2048 nt
	v_lshl_add_u64 v[88:89], v[76:77], 0, v[88:89]
	global_load_dwordx4 v[94:97], v[94:95], off offset:3072 nt
	v_lshl_add_u64 v[86:87], v[78:79], 0, v[86:87]
	s_waitcnt vmcnt(0)
	v_and_b32_e32 v99, 0xffff0000, v56
	v_and_b32_e32 v101, 0xffff0000, v58
	v_lshlrev_b32_e32 v98, 16, v56
	v_lshlrev_b32_e32 v100, 16, v58
	v_and_b32_e32 v103, 0xffff0000, v60
	v_lshlrev_b32_e32 v56, 16, v57
	v_lshlrev_b32_e32 v71, 16, v68
	v_and_b32_e32 v115, 0xffff0000, v68
	v_lshlrev_b32_e32 v117, 16, v69
	v_and_b32_e32 v119, 0xffff0000, v69
	v_mul_f32_e32 v68, v99, v99
	v_mul_f32_e32 v69, v101, v101
	v_lshlrev_b32_e32 v58, 16, v59
	v_lshlrev_b32_e32 v102, 16, v60
	v_and_b32_e32 v105, 0xffff0000, v62
	v_mul_f32_e32 v73, v103, v103
	v_fmac_f32_e32 v68, v98, v98
	v_fmac_f32_e32 v69, v100, v100
	v_and_b32_e32 v57, 0xffff0000, v57
	v_and_b32_e32 v59, 0xffff0000, v59
	v_lshlrev_b32_e32 v60, 16, v61
	v_lshlrev_b32_e32 v104, 16, v62
	v_and_b32_e32 v109, 0xffff0000, v64
	v_and_b32_e32 v108, 0xffff0000, v66
	v_lshlrev_b32_e32 v70, 16, v84
	v_and_b32_e32 v114, 0xffff0000, v84
	v_mul_f32_e32 v84, v105, v105
	v_fmac_f32_e32 v73, v102, v102
	v_fmac_f32_e32 v68, v56, v56
	v_fmac_f32_e32 v69, v58, v58
	v_and_b32_e32 v61, 0xffff0000, v61
	v_lshlrev_b32_e32 v62, 16, v63
	v_lshlrev_b32_e32 v107, 16, v64
	v_lshlrev_b32_e32 v106, 16, v66
	v_lshlrev_b32_e32 v111, 16, v65
	v_and_b32_e32 v113, 0xffff0000, v65
	v_pk_mul_f32 v[64:65], v[108:109], v[108:109]
	v_fmac_f32_e32 v84, v104, v104
	v_fmac_f32_e32 v73, v60, v60
	v_fmac_f32_e32 v68, v57, v57
	v_fmac_f32_e32 v69, v59, v59
	v_and_b32_e32 v63, 0xffff0000, v63
	v_lshlrev_b32_e32 v110, 16, v67
	v_pk_fma_f32 v[64:65], v[106:107], v[106:107], v[64:65]
	v_fmac_f32_e32 v84, v62, v62
	v_fmac_f32_e32 v73, v61, v61
	v_add_f32_e32 v68, v68, v69
	v_and_b32_e32 v112, 0xffff0000, v67
	v_pk_mul_f32 v[66:67], v[114:115], v[114:115]
	v_pk_fma_f32 v[64:65], v[110:111], v[110:111], v[64:65]
	v_fmac_f32_e32 v84, v63, v63
	v_add_f32_e32 v68, v68, v73
	v_lshlrev_b32_e32 v116, 16, v85
	v_pk_fma_f32 v[66:67], v[70:71], v[70:71], v[66:67]
	v_pk_fma_f32 v[64:65], v[112:113], v[112:113], v[64:65]
	v_add_f32_e32 v68, v68, v84
	v_and_b32_e32 v118, 0xffff0000, v85
	v_pk_fma_f32 v[66:67], v[116:117], v[116:117], v[66:67]
	v_add_f32_e32 v64, v68, v64
	v_pk_fma_f32 v[66:67], v[118:119], v[118:119], v[66:67]
	v_add_f32_e32 v64, v64, v65
	v_add_f32_e32 v64, v64, v66
	v_add_f32_e32 v64, v64, v67
	ds_bpermute_b32 v65, v83, v64
	v_mov_b32_e32 v124, v106
	v_mov_b32_e32 v126, v110
	v_mov_b32_e32 v127, v112
	v_mov_b32_e32 v112, v111
	s_waitcnt lgkmcnt(0)
	v_add_f32_e32 v64, v64, v65
	ds_bpermute_b32 v65, v132, v64
	s_waitcnt lgkmcnt(0)
	v_add_f32_e32 v64, v64, v65
	ds_bpermute_b32 v65, v133, v64
	s_waitcnt lgkmcnt(0)
	v_add_f32_e32 v66, v64, v65
	v_add_u32_e32 v64, 1, v72
	ds_bpermute_b32 v67, v134, v66
	v_ashrrev_i32_e32 v65, 31, v64
	v_lshlrev_b64 v[84:85], 12, v[64:65]
	v_lshl_add_u64 v[68:69], v[74:75], 0, v[84:85]
	global_load_dwordx2 v[120:121], v[68:69], off
	global_load_dwordx2 v[122:123], v[68:69], off offset:512
	global_load_dwordx2 v[138:139], v[68:69], off offset:1024
	global_load_dwordx2 v[140:141], v[68:69], off offset:1536
	s_waitcnt lgkmcnt(0)
	v_add_f32_e32 v66, v66, v67
	ds_bpermute_b32 v67, v135, v66
	v_add_u32_e32 v72, s13, v72
	s_waitcnt lgkmcnt(0)
	v_add_f32_e32 v73, v66, v67
	global_load_dwordx2 v[142:143], v[68:69], off offset:2048
	global_load_dwordx2 v[144:145], v[68:69], off offset:2560
	global_load_dwordx2 v[66:67], v[68:69], off offset:3072
	s_nop 0
	global_load_dwordx2 v[68:69], v[68:69], off offset:3584
	ds_bpermute_b32 v125, v136, v73
	s_waitcnt lgkmcnt(0)
	v_add_f32_e32 v73, v73, v125
	v_fmamk_f32 v73, v73, 0x3a000000, v82
	v_mul_f32_e32 v106, 0x4b800000, v73
	v_cmp_gt_f32_e32 vcc, s14, v73
	v_mov_b32_e32 v125, v108
	v_mov_b32_e32 v108, v107
	v_cndmask_b32_e32 v73, v73, v106, vcc
	v_rsq_f32_e32 v73, v73
	s_waitcnt vmcnt(7)
	v_and_b32_e32 v164, 0xffff0000, v120
	v_mul_f32_e32 v106, 0x45800000, v73
	v_cndmask_b32_e32 v106, v73, v106, vcc
	v_pk_mul_f32 v[98:99], v[98:99], v[106:107] op_sel_hi:[1,0]
	v_pk_mul_f32 v[102:103], v[102:103], v[106:107] op_sel_hi:[1,0]
	v_pk_mul_f32 v[124:125], v[124:125], v[106:107] op_sel_hi:[1,0]
	v_pk_mul_f32 v[56:57], v[56:57], v[106:107] op_sel_hi:[1,0]
	v_pk_mul_f32 v[128:129], v[60:61], v[106:107] op_sel_hi:[1,0]
	v_pk_mul_f32 v[126:127], v[126:127], v[106:107] op_sel_hi:[1,0]
	v_pk_fma_f32 v[60:61], v[0:1], v[98:99], v[52:53]
	v_pk_fma_f32 v[52:53], v[8:9], v[102:103], v[44:45]
	v_pk_fma_f32 v[44:45], v[16:17], v[124:125], v[36:37]
	v_pk_mul_f32 v[36:37], v[108:109], v[106:107] op_sel_hi:[1,0]
	v_pk_mul_f32 v[130:131], v[62:63], v[106:107] op_sel_hi:[1,0]
	v_pk_fma_f32 v[62:63], v[2:3], v[56:57], v[54:55]
	v_pk_fma_f32 v[54:55], v[10:11], v[128:129], v[46:47]
	v_pk_fma_f32 v[46:47], v[18:19], v[126:127], v[38:39]
	v_pk_mul_f32 v[38:39], v[112:113], v[106:107] op_sel_hi:[1,0]
	v_pk_fma_f32 v[32:33], v[20:21], v[36:37], v[32:33]
	v_pk_mul_f32 v[100:101], v[100:101], v[106:107] op_sel_hi:[1,0]
	v_pk_fma_f32 v[34:35], v[22:23], v[38:39], v[34:35]
	v_mov_b32_e32 v38, v33
	v_mov_b32_e32 v39, v45
	v_pk_mul_f32 v[58:59], v[58:59], v[106:107] op_sel_hi:[1,0]
	v_pk_fma_f32 v[56:57], v[4:5], v[100:101], v[48:49]
	v_mov_b32_e32 v36, v32
	v_mov_b32_e32 v37, v44
	v_pk_mul_f32 v[38:39], v[38:39], v[38:39]
	v_pk_fma_f32 v[58:59], v[6:7], v[58:59], v[50:51]
	v_pk_fma_f32 v[50:51], v[14:15], v[130:131], v[42:43]
	v_pk_fma_f32 v[36:37], v[36:37], v[36:37], v[38:39]
	v_mov_b32_e32 v38, v34
	v_mov_b32_e32 v39, v46
	s_waitcnt vmcnt(6)
	v_and_b32_e32 v130, 0xffff0000, v122
	v_mov_b32_e32 v165, v61
	v_mov_b32_e32 v131, v57
	v_pk_fma_f32 v[36:37], v[38:39], v[38:39], v[36:37]
	v_mov_b32_e32 v38, v35
	v_mov_b32_e32 v39, v47
	v_lshlrev_b32_e32 v162, 16, v120
	v_lshlrev_b32_e32 v126, 16, v122
	v_mov_b32_e32 v163, v60
	v_pk_mul_f32 v[100:101], v[164:165], v[164:165]
	v_mov_b32_e32 v127, v56
	v_pk_mul_f32 v[102:103], v[130:131], v[130:131]
	v_pk_mul_f32 v[104:105], v[104:105], v[106:107] op_sel_hi:[1,0]
	v_pk_fma_f32 v[146:147], v[38:39], v[38:39], v[36:37]
	v_mov_b32_e32 v36, v70
	v_mov_b32_e32 v37, v114
	v_mov_b32_e32 v114, v71
	v_lshlrev_b32_e32 v166, 16, v121
	v_lshlrev_b32_e32 v124, 16, v123
	v_pk_fma_f32 v[100:101], v[162:163], v[162:163], v[100:101]
	v_mov_b32_e32 v167, v62
	v_pk_fma_f32 v[102:103], v[126:127], v[126:127], v[102:103]
	v_mov_b32_e32 v125, v58
	v_pk_fma_f32 v[48:49], v[12:13], v[104:105], v[40:41]
	v_pk_mul_f32 v[36:37], v[36:37], v[106:107] op_sel_hi:[1,0]
	v_pk_mul_f32 v[40:41], v[114:115], v[106:107] op_sel_hi:[1,0]
	v_and_b32_e32 v168, 0xffff0000, v121
	v_and_b32_e32 v128, 0xffff0000, v123
	v_pk_fma_f32 v[100:101], v[166:167], v[166:167], v[100:101]
	v_mov_b32_e32 v169, v63
	v_pk_fma_f32 v[102:103], v[124:125], v[124:125], v[102:103]
	v_mov_b32_e32 v129, v59
	v_mov_b32_e32 v38, v116
	v_mov_b32_e32 v39, v118
	v_pk_fma_f32 v[36:37], v[24:25], v[36:37], v[90:91]
	v_mov_b32_e32 v118, v117
	v_pk_fma_f32 v[40:41], v[28:29], v[40:41], v[94:95]
	s_waitcnt vmcnt(5)
	v_and_b32_e32 v122, 0xffff0000, v138
	v_pk_fma_f32 v[100:101], v[168:169], v[168:169], v[100:101]
	v_pk_fma_f32 v[102:103], v[128:129], v[128:129], v[102:103]
	v_mov_b32_e32 v123, v53
	v_pk_mul_f32 v[38:39], v[38:39], v[106:107] op_sel_hi:[1,0]
	v_pk_mul_f32 v[42:43], v[118:119], v[106:107] op_sel_hi:[1,0]
	v_mov_b32_e32 v90, v41
	v_mov_b32_e32 v91, v37
	v_lshlrev_b32_e32 v118, 16, v138
	v_pk_add_f32 v[100:101], v[100:101], v[102:103]
	v_mov_b32_e32 v119, v52
	v_pk_mul_f32 v[102:103], v[122:123], v[122:123]
	v_pk_fma_f32 v[38:39], v[26:27], v[38:39], v[92:93]
	v_pk_fma_f32 v[42:43], v[30:31], v[42:43], v[96:97]
	v_mov_b32_e32 v70, v40
	v_mov_b32_e32 v71, v36
	v_pk_mul_f32 v[90:91], v[90:91], v[90:91]
	v_lshlrev_b32_e32 v116, 16, v139
	v_pk_fma_f32 v[102:103], v[118:119], v[118:119], v[102:103]
	v_mov_b32_e32 v117, v54
	v_pk_fma_f32 v[70:71], v[70:71], v[70:71], v[90:91]
	v_mov_b32_e32 v90, v42
	v_mov_b32_e32 v91, v38
	v_and_b32_e32 v120, 0xffff0000, v139
	v_pk_fma_f32 v[102:103], v[116:117], v[116:117], v[102:103]
	v_mov_b32_e32 v121, v55
	v_pk_fma_f32 v[70:71], v[90:91], v[90:91], v[70:71]
	v_mov_b32_e32 v90, v43
	v_mov_b32_e32 v91, v39
	s_waitcnt vmcnt(4)
	v_and_b32_e32 v114, 0xffff0000, v140
	s_waitcnt vmcnt(2)
	v_and_b32_e32 v95, 0xffff0000, v144
	v_and_b32_e32 v94, 0xffff0000, v142
	v_pk_fma_f32 v[102:103], v[120:121], v[120:121], v[102:103]
	v_mov_b32_e32 v115, v49
	v_pk_fma_f32 v[70:71], v[90:91], v[90:91], v[70:71]
	v_lshlrev_b32_e32 v110, 16, v140
	v_lshlrev_b32_e32 v91, 16, v144
	v_lshlrev_b32_e32 v90, 16, v142
	v_pk_mul_f32 v[92:93], v[94:95], v[94:95]
	v_pk_add_f32 v[100:101], v[102:103], v[100:101]
	v_mov_b32_e32 v111, v48
	v_pk_mul_f32 v[102:103], v[114:115], v[114:115]
	v_lshlrev_b32_e32 v108, 16, v141
	v_lshlrev_b32_e32 v97, 16, v145
	v_lshlrev_b32_e32 v96, 16, v143
	v_pk_fma_f32 v[92:93], v[90:91], v[90:91], v[92:93]
	v_pk_fma_f32 v[102:103], v[110:111], v[110:111], v[102:103]
	v_mov_b32_e32 v109, v50
	v_and_b32_e32 v112, 0xffff0000, v141
	v_and_b32_e32 v99, 0xffff0000, v145
	v_and_b32_e32 v98, 0xffff0000, v143
	v_pk_fma_f32 v[92:93], v[96:97], v[96:97], v[92:93]
	v_pk_fma_f32 v[102:103], v[108:109], v[108:109], v[102:103]
	v_mov_b32_e32 v113, v51
	v_pk_fma_f32 v[92:93], v[98:99], v[98:99], v[92:93]
	v_pk_fma_f32 v[102:103], v[112:113], v[112:113], v[102:103]
	s_waitcnt vmcnt(1)
	v_lshlrev_b32_e32 v104, 16, v67
	v_pk_add_f32 v[100:101], v[102:103], v[100:101]
	v_mov_b32_e32 v102, v92
	v_mov_b32_e32 v103, v147
	v_pk_add_f32 v[138:139], v[100:101], v[102:103]
	s_waitcnt vmcnt(0)
	v_and_b32_e32 v103, 0xffff0000, v68
	v_and_b32_e32 v102, 0xffff0000, v66
	v_lshlrev_b32_e32 v101, 16, v68
	v_lshlrev_b32_e32 v100, 16, v66
	v_and_b32_e32 v106, 0xffff0000, v67
	v_pk_mul_f32 v[66:67], v[102:103], v[102:103]
	v_lshlrev_b32_e32 v105, 16, v69
	v_pk_fma_f32 v[66:67], v[100:101], v[100:101], v[66:67]
	v_and_b32_e32 v107, 0xffff0000, v69
	v_pk_fma_f32 v[66:67], v[104:105], v[104:105], v[66:67]
	v_pk_mov_b32 v[68:69], v[92:93], v[146:147] op_sel:[1,0]
	v_pk_fma_f32 v[66:67], v[106:107], v[106:107], v[66:67]
	v_pk_add_f32 v[68:69], v[138:139], v[68:69]
	v_mov_b32_e32 v92, v66
	v_mov_b32_e32 v93, v71
	v_pk_add_f32 v[68:69], v[68:69], v[92:93]
	v_lshlrev_b64 v[92:93], 13, v[64:65]
	v_lshl_add_u64 v[64:65], v[80:81], 0, v[92:93]
	v_pk_mov_b32 v[66:67], v[66:67], v[70:71] op_sel:[1,0]
	global_load_dwordx4 v[138:141], v[64:65], off nt
	global_load_dwordx4 v[142:145], v[64:65], off offset:1024 nt
	global_load_dwordx4 v[146:149], v[64:65], off offset:2048 nt
	global_load_dwordx4 v[150:153], v[64:65], off offset:3072 nt
	v_pk_add_f32 v[66:67], v[68:69], v[66:67]
	ds_bpermute_b32 v69, v83, v67
	ds_bpermute_b32 v68, v83, v66
	v_add_co_u32_e32 v64, vcc, s3, v64
	v_mov_b32_e32 v163, v164
	s_nop 0
	v_addc_co_u32_e32 v65, vcc, 0, v65, vcc
	s_waitcnt lgkmcnt(0)
	v_pk_add_f32 v[66:67], v[66:67], v[68:69]
	ds_bpermute_b32 v69, v132, v67
	ds_bpermute_b32 v68, v132, v66
	v_mov_b32_e32 v127, v130
	v_mov_b32_e32 v167, v168
	v_mov_b32_e32 v125, v128
	v_mov_b32_e32 v119, v122
	s_waitcnt lgkmcnt(0)
	v_pk_add_f32 v[66:67], v[66:67], v[68:69]
	ds_bpermute_b32 v69, v133, v67
	ds_bpermute_b32 v68, v133, v66
	v_mov_b32_e32 v117, v120
	v_mov_b32_e32 v111, v114
	v_mov_b32_e32 v109, v112
	s_waitcnt lgkmcnt(0)
	v_pk_add_f32 v[170:171], v[66:67], v[68:69]
	global_load_dwordx4 v[154:157], v[64:65], off nt
	global_load_dwordx4 v[158:161], v[64:65], off offset:1024 nt
	global_load_dwordx4 v[68:71], v[64:65], off offset:2048 nt
	s_nop 0
	global_load_dwordx4 v[64:67], v[64:65], off offset:3072 nt
	ds_bpermute_b32 v173, v134, v171
	ds_bpermute_b32 v172, v134, v170
	global_store_dwordx4 v[88:89], v[60:63], off nt
	global_store_dwordx4 v[88:89], v[56:59], off offset:1024 nt
	global_store_dwordx4 v[88:89], v[52:55], off offset:2048 nt
	global_store_dwordx4 v[88:89], v[48:51], off offset:3072 nt
	v_add_co_u32_e32 v88, vcc, s3, v88
	s_waitcnt lgkmcnt(0)
	v_pk_add_f32 v[170:171], v[170:171], v[172:173]
	ds_bpermute_b32 v173, v135, v171
	ds_bpermute_b32 v172, v135, v170
	v_addc_co_u32_e32 v89, vcc, 0, v89, vcc
	global_store_dwordx4 v[88:89], v[44:47], off nt
	global_store_dwordx4 v[88:89], v[32:35], off offset:1024 nt
	global_store_dwordx4 v[88:89], v[36:39], off offset:2048 nt
	global_store_dwordx4 v[88:89], v[40:43], off offset:3072 nt
	s_waitcnt lgkmcnt(0)
	v_pk_add_f32 v[170:171], v[170:171], v[172:173]
	ds_bpermute_b32 v173, v136, v171
	ds_bpermute_b32 v172, v136, v170
	s_waitcnt lgkmcnt(0)
	v_pk_add_f32 v[170:171], v[170:171], v[172:173]
	s_nop 0
	v_pk_fma_f32 v[170:171], v[170:171], s[12:13], v[82:83] op_sel_hi:[1,0,0]
	s_nop 0
	v_mul_f32_e32 v73, 0x4b800000, v171
	v_cmp_gt_f32_e32 vcc, s14, v171
	s_nop 1
	v_cndmask_b32_e32 v73, v171, v73, vcc
	v_rsq_f32_e32 v73, v73
	s_nop 0
	v_mul_f32_e32 v88, 0x45800000, v73
	v_cndmask_b32_e32 v88, v73, v88, vcc
	v_pk_mul_f32 v[44:45], v[44:45], v[88:89] op_sel_hi:[1,0]
	v_pk_mul_f32 v[48:49], v[48:49], v[88:89] op_sel_hi:[1,0]
	v_pk_mul_f32 v[50:51], v[50:51], v[88:89] op_sel_hi:[1,0]
	v_cvt_pk_bf16_f32 v44, v44, v45
	v_mul_f32_e32 v45, 0x4b800000, v170
	v_cmp_gt_f32_e32 vcc, s14, v170
	v_cvt_pk_bf16_f32 v48, v48, v49
	v_cvt_pk_bf16_f32 v49, v50, v51
	v_cndmask_b32_e32 v45, v170, v45, vcc
	global_store_dwordx2 v[86:87], v[48:49], off offset:1536
	v_rsq_f32_e32 v48, v45
	v_pk_mul_f32 v[46:47], v[46:47], v[88:89] op_sel_hi:[1,0]
	v_pk_mul_f32 v[52:53], v[52:53], v[88:89] op_sel_hi:[1,0]
	v_cvt_pk_bf16_f32 v45, v46, v47
	global_store_dwordx2 v[86:87], v[44:45], off offset:2048
	v_mul_f32_e32 v44, 0x45800000, v48
	v_cndmask_b32_e32 v170, v48, v44, vcc
	v_pk_mul_f32 v[54:55], v[54:55], v[88:89] op_sel_hi:[1,0]
	v_pk_mul_f32 v[44:45], v[162:163], v[170:171] op_sel_hi:[1,0]
	v_pk_mul_f32 v[48:49], v[126:127], v[170:171] op_sel_hi:[1,0]
	v_cvt_pk_bf16_f32 v52, v52, v53
	v_cvt_pk_bf16_f32 v53, v54, v55
	s_waitcnt vmcnt(17)
	v_pk_fma_f32 v[44:45], v[0:1], v[44:45], v[138:139]
	s_waitcnt vmcnt(16)
	v_pk_fma_f32 v[48:49], v[4:5], v[48:49], v[142:143]
	global_store_dwordx2 v[86:87], v[52:53], off offset:1024
	v_pk_mul_f32 v[46:47], v[166:167], v[170:171] op_sel_hi:[1,0]
	v_mul_f32_e32 v52, v45, v45
	v_pk_mul_f32 v[50:51], v[124:125], v[170:171] op_sel_hi:[1,0]
	v_mul_f32_e32 v53, v49, v49
	v_pk_fma_f32 v[46:47], v[2:3], v[46:47], v[140:141]
	v_fmac_f32_e32 v52, v44, v44
	v_pk_fma_f32 v[50:51], v[6:7], v[50:51], v[144:145]
	v_fmac_f32_e32 v53, v48, v48
	v_pk_mul_f32 v[56:57], v[56:57], v[88:89] op_sel_hi:[1,0]
	v_pk_mul_f32 v[58:59], v[58:59], v[88:89] op_sel_hi:[1,0]
	v_fmac_f32_e32 v52, v46, v46
	v_fmac_f32_e32 v53, v50, v50
	v_cvt_pk_bf16_f32 v56, v56, v57
	v_cvt_pk_bf16_f32 v57, v58, v59
	v_fmac_f32_e32 v52, v47, v47
	v_fmac_f32_e32 v53, v51, v51
	global_store_dwordx2 v[86:87], v[56:57], off offset:512
	v_add_f32_e32 v56, v52, v53
	v_pk_mul_f32 v[52:53], v[118:119], v[170:171] op_sel_hi:[1,0]
	v_pk_mul_f32 v[54:55], v[116:117], v[170:171] op_sel_hi:[1,0]
	s_waitcnt vmcnt(17)
	v_pk_fma_f32 v[52:53], v[8:9], v[52:53], v[146:147]
	v_pk_fma_f32 v[54:55], v[10:11], v[54:55], v[148:149]
	v_mul_f32_e32 v57, v53, v53
	v_fmac_f32_e32 v57, v52, v52
	v_pk_mul_f32 v[60:61], v[60:61], v[88:89] op_sel_hi:[1,0]
	v_pk_mul_f32 v[62:63], v[62:63], v[88:89] op_sel_hi:[1,0]
	v_fmac_f32_e32 v57, v54, v54
	v_cvt_pk_bf16_f32 v60, v60, v61
	v_cvt_pk_bf16_f32 v61, v62, v63
	v_fmac_f32_e32 v57, v55, v55
	global_store_dwordx2 v[86:87], v[60:61], off
	v_add_f32_e32 v60, v57, v56
	v_pk_mul_f32 v[56:57], v[110:111], v[170:171] op_sel_hi:[1,0]
	v_pk_mul_f32 v[58:59], v[108:109], v[170:171] op_sel_hi:[1,0]
	s_waitcnt vmcnt(17)
	v_pk_fma_f32 v[56:57], v[12:13], v[56:57], v[150:151]
	v_pk_fma_f32 v[58:59], v[14:15], v[58:59], v[152:153]
	v_mul_f32_e32 v61, v57, v57
	v_fmac_f32_e32 v61, v56, v56
	v_fmac_f32_e32 v61, v58, v58
	v_fmac_f32_e32 v61, v59, v59
	v_add_f32_e32 v73, v61, v60
	v_mov_b32_e32 v60, v90
	v_mov_b32_e32 v61, v94
	v_mov_b32_e32 v63, v98
	v_mov_b32_e32 v94, v91
	v_mov_b32_e32 v98, v97
	v_pk_mul_f32 v[60:61], v[60:61], v[170:171] op_sel_hi:[1,0]
	v_pk_mul_f32 v[90:91], v[94:95], v[170:171] op_sel_hi:[1,0]
	v_pk_mul_f32 v[94:95], v[98:99], v[170:171] op_sel_hi:[1,0]
	v_mov_b32_e32 v62, v96
	s_waitcnt vmcnt(16)
	v_pk_fma_f32 v[60:61], v[16:17], v[60:61], v[154:155]
	s_waitcnt vmcnt(15)
	v_pk_fma_f32 v[96:97], v[22:23], v[94:95], v[160:161]
	v_pk_fma_f32 v[94:95], v[20:21], v[90:91], v[158:159]
	v_pk_mul_f32 v[62:63], v[62:63], v[170:171] op_sel_hi:[1,0]
	v_mov_b32_e32 v98, v95
	v_mov_b32_e32 v99, v61
	v_pk_fma_f32 v[62:63], v[18:19], v[62:63], v[156:157]
	v_mov_b32_e32 v90, v94
	v_mov_b32_e32 v91, v60
	v_pk_mul_f32 v[98:99], v[98:99], v[98:99]
	s_nop 0
	v_pk_fma_f32 v[90:91], v[90:91], v[90:91], v[98:99]
	v_mov_b32_e32 v98, v96
	v_mov_b32_e32 v99, v62
	v_pk_fma_f32 v[90:91], v[98:99], v[98:99], v[90:91]
	v_mov_b32_e32 v98, v97
	v_mov_b32_e32 v99, v63
	v_pk_fma_f32 v[90:91], v[98:99], v[98:99], v[90:91]
	v_mov_b32_e32 v98, v104
	v_add_f32_e32 v73, v91, v73
	v_add_f32_e32 v73, v90, v73
	v_mov_b32_e32 v90, v100
	v_mov_b32_e32 v91, v102
	v_pk_mul_f32 v[90:91], v[90:91], v[170:171] op_sel_hi:[1,0]
	v_mov_b32_e32 v99, v106
	v_mov_b32_e32 v102, v101
	v_pk_mul_f32 v[98:99], v[98:99], v[170:171] op_sel_hi:[1,0]
	s_waitcnt vmcnt(14)
	v_pk_fma_f32 v[68:69], v[24:25], v[90:91], v[68:69]
	v_pk_mul_f32 v[90:91], v[102:103], v[170:171] op_sel_hi:[1,0]
	v_mov_b32_e32 v106, v105
	v_pk_fma_f32 v[70:71], v[26:27], v[98:99], v[70:71]
	v_pk_mul_f32 v[98:99], v[106:107], v[170:171] op_sel_hi:[1,0]
	s_waitcnt vmcnt(13)
	v_pk_fma_f32 v[64:65], v[28:29], v[90:91], v[64:65]
	v_pk_fma_f32 v[66:67], v[30:31], v[98:99], v[66:67]
	v_mov_b32_e32 v98, v65
	v_mov_b32_e32 v99, v69
	v_mov_b32_e32 v90, v64
	v_mov_b32_e32 v91, v68
	v_pk_mul_f32 v[98:99], v[98:99], v[98:99]
	s_nop 0
	v_pk_fma_f32 v[90:91], v[90:91], v[90:91], v[98:99]
	v_mov_b32_e32 v98, v66
	v_mov_b32_e32 v99, v70
	v_pk_fma_f32 v[90:91], v[98:99], v[98:99], v[90:91]
	v_mov_b32_e32 v98, v67
	v_mov_b32_e32 v99, v71
	v_pk_fma_f32 v[90:91], v[98:99], v[98:99], v[90:91]
	s_nop 0
	v_add_f32_e32 v73, v91, v73
	v_add_f32_e32 v73, v90, v73
	ds_bpermute_b32 v89, v83, v73
	s_waitcnt lgkmcnt(0)
	v_add_f32_e32 v73, v73, v89
	v_pk_mul_f32 v[32:33], v[32:33], v[88:89] op_sel_hi:[1,0]
	v_pk_mul_f32 v[34:35], v[34:35], v[88:89] op_sel_hi:[1,0]
	ds_bpermute_b32 v89, v132, v73
	v_cvt_pk_bf16_f32 v32, v32, v33
	v_cvt_pk_bf16_f32 v33, v34, v35
	global_store_dwordx2 v[86:87], v[32:33], off offset:2560
	s_waitcnt lgkmcnt(0)
	v_pk_mul_f32 v[32:33], v[36:37], v[88:89] op_sel_hi:[1,0]
	v_add_f32_e32 v36, v73, v89
	ds_bpermute_b32 v37, v133, v36
	v_pk_mul_f32 v[34:35], v[38:39], v[88:89] op_sel_hi:[1,0]
	v_cvt_pk_bf16_f32 v32, v32, v33
	v_cvt_pk_bf16_f32 v33, v34, v35
	global_store_dwordx2 v[86:87], v[32:33], off offset:3072
	s_waitcnt lgkmcnt(0)
	v_add_f32_e32 v36, v36, v37
	ds_bpermute_b32 v37, v134, v36
	v_pk_mul_f32 v[32:33], v[40:41], v[88:89] op_sel_hi:[1,0]
	v_pk_mul_f32 v[34:35], v[42:43], v[88:89] op_sel_hi:[1,0]
	v_cvt_pk_bf16_f32 v32, v32, v33
	v_cvt_pk_bf16_f32 v33, v34, v35
	s_waitcnt lgkmcnt(0)
	v_add_f32_e32 v34, v36, v37
	ds_bpermute_b32 v35, v135, v34
	global_store_dwordx2 v[86:87], v[32:33], off offset:3584
	v_lshl_add_u64 v[32:33], v[76:77], 0, v[92:93]
	global_store_dwordx4 v[32:33], v[44:47], off nt
	global_store_dwordx4 v[32:33], v[48:51], off offset:1024 nt
	global_store_dwordx4 v[32:33], v[52:55], off offset:2048 nt
	global_store_dwordx4 v[32:33], v[56:59], off offset:3072 nt
	v_add_co_u32_e32 v32, vcc, s3, v32
	s_waitcnt lgkmcnt(0)
	v_add_f32_e32 v34, v34, v35
	ds_bpermute_b32 v35, v136, v34
	v_addc_co_u32_e32 v33, vcc, 0, v33, vcc
	global_store_dwordx4 v[32:33], v[60:63], off nt
	global_store_dwordx4 v[32:33], v[94:97], off offset:1024 nt
	global_store_dwordx4 v[32:33], v[68:71], off offset:2048 nt
	global_store_dwordx4 v[32:33], v[64:67], off offset:3072 nt
	s_waitcnt lgkmcnt(0)
	v_add_f32_e32 v34, v34, v35
	v_fmamk_f32 v34, v34, 0x3a000000, v82
	v_mul_f32_e32 v35, 0x4b800000, v34
	v_cmp_gt_f32_e32 vcc, s14, v34
	s_nop 1
	v_cndmask_b32_e32 v34, v34, v35, vcc
	v_rsq_f32_e32 v34, v34
	s_nop 0
	v_mul_f32_e32 v32, 0x45800000, v34
	v_cndmask_b32_e32 v32, v34, v32, vcc
	v_pk_mul_f32 v[36:37], v[44:45], v[32:33] op_sel_hi:[1,0]
	v_pk_mul_f32 v[38:39], v[46:47], v[32:33] op_sel_hi:[1,0]
	v_lshl_add_u64 v[34:35], v[78:79], 0, v[84:85]
	v_cvt_pk_bf16_f32 v36, v36, v37
	v_cvt_pk_bf16_f32 v37, v38, v39
	global_store_dwordx2 v[34:35], v[36:37], off
	v_pk_mul_f32 v[36:37], v[48:49], v[32:33] op_sel_hi:[1,0]
	v_pk_mul_f32 v[38:39], v[50:51], v[32:33] op_sel_hi:[1,0]
	v_cvt_pk_bf16_f32 v36, v36, v37
	v_cvt_pk_bf16_f32 v37, v38, v39
	global_store_dwordx2 v[34:35], v[36:37], off offset:512
	v_pk_mul_f32 v[36:37], v[52:53], v[32:33] op_sel_hi:[1,0]
	v_pk_mul_f32 v[38:39], v[54:55], v[32:33] op_sel_hi:[1,0]
	v_cvt_pk_bf16_f32 v36, v36, v37
	v_cvt_pk_bf16_f32 v37, v38, v39
	global_store_dwordx2 v[34:35], v[36:37], off offset:1024
	v_pk_mul_f32 v[36:37], v[56:57], v[32:33] op_sel_hi:[1,0]
	v_pk_mul_f32 v[38:39], v[58:59], v[32:33] op_sel_hi:[1,0]
	v_cvt_pk_bf16_f32 v36, v36, v37
	v_cvt_pk_bf16_f32 v37, v38, v39
	global_store_dwordx2 v[34:35], v[36:37], off offset:1536
	v_pk_mul_f32 v[36:37], v[60:61], v[32:33] op_sel_hi:[1,0]
	v_pk_mul_f32 v[38:39], v[62:63], v[32:33] op_sel_hi:[1,0]
	v_cvt_pk_bf16_f32 v36, v36, v37
	v_cvt_pk_bf16_f32 v37, v38, v39
	global_store_dwordx2 v[34:35], v[36:37], off offset:2048
	v_pk_mul_f32 v[36:37], v[94:95], v[32:33] op_sel_hi:[1,0]
	v_pk_mul_f32 v[38:39], v[96:97], v[32:33] op_sel_hi:[1,0]
	v_cvt_pk_bf16_f32 v36, v36, v37
	v_cvt_pk_bf16_f32 v37, v38, v39
	global_store_dwordx2 v[34:35], v[36:37], off offset:2560
	v_pk_mul_f32 v[36:37], v[68:69], v[32:33] op_sel_hi:[1,0]
	v_pk_mul_f32 v[38:39], v[70:71], v[32:33] op_sel_hi:[1,0]
	v_cvt_pk_bf16_f32 v36, v36, v37
	v_cvt_pk_bf16_f32 v37, v38, v39
	global_store_dwordx2 v[34:35], v[36:37], off offset:3072
	v_pk_mul_f32 v[36:37], v[64:65], v[32:33] op_sel_hi:[1,0]
	v_pk_mul_f32 v[32:33], v[66:67], v[32:33] op_sel_hi:[1,0]
	v_cmp_lt_i32_e32 vcc, s15, v72
	v_cvt_pk_bf16_f32 v36, v36, v37
	v_cvt_pk_bf16_f32 v37, v32, v33
	s_or_b64 s[10:11], vcc, s[10:11]
	global_store_dwordx2 v[34:35], v[36:37], off offset:3584
	s_andn2_b64 exec, exec, s[10:11]
	s_cbranch_execnz .LBB0_756

.LBB0_1491:
	v_ashrrev_i32_e32 v49, 31, v48
	v_lshlrev_b64 v[32:33], 12, v[48:49]
	v_lshl_add_u64 v[32:33], v[50:51], 0, v[32:33]
	v_add_u32_e32 v44, 1, v48
	global_load_dwordx2 v[46:47], v[32:33], off offset:2560
	global_load_dwordx2 v[56:57], v[32:33], off offset:2048
	global_load_dwordx2 v[58:59], v[32:33], off offset:3584
	global_load_dwordx2 v[60:61], v[32:33], off offset:3072
	global_load_dwordx2 v[62:63], v[32:33], off
	global_load_dwordx2 v[76:77], v[32:33], off offset:512
	global_load_dwordx2 v[104:105], v[32:33], off offset:1024
	v_ashrrev_i32_e32 v45, 31, v44
	v_lshlrev_b64 v[34:35], 12, v[44:45]
	v_lshl_add_u64 v[64:65], v[50:51], 0, v[34:35]
	global_load_dwordx2 v[106:107], v[64:65], off offset:2560
	global_load_dwordx2 v[108:109], v[64:65], off offset:2048
	global_load_dwordx2 v[110:111], v[64:65], off
	global_load_dwordx2 v[112:113], v[64:65], off offset:512
	global_load_dwordx2 v[114:115], v[64:65], off offset:1024
	global_load_dwordx2 v[122:123], v[64:65], off offset:1536
	global_load_dwordx2 v[120:121], v[32:33], off offset:1536
	v_lshlrev_b64 v[32:33], 13, v[48:49]
	v_lshl_add_u64 v[100:101], v[52:53], 0, v[32:33]
	global_load_dwordx4 v[40:43], v[100:101], off nt
	global_load_dwordx4 v[36:39], v[100:101], off offset:1024 nt
	global_load_dwordx4 v[32:35], v[100:101], off offset:2048 nt
	global_load_dwordx2 v[130:131], v[64:65], off offset:3072
	global_load_dwordx2 v[132:133], v[64:65], off offset:3584
	v_add_co_u32_e32 v178, vcc, s3, v100
	v_lshlrev_b64 v[44:45], 13, v[44:45]
	s_nop 0
	v_addc_co_u32_e32 v179, vcc, 0, v101, vcc
	v_lshl_add_u64 v[180:181], v[52:53], 0, v[44:45]
	v_add_u32_e32 v48, s4, v48
	s_waitcnt vmcnt(0)
	v_and_b32_e32 v83, 0xffff0000, v46
	v_lshlrev_b32_e32 v78, 16, v56
	v_and_b32_e32 v67, 0xffff0000, v58
	v_and_b32_e32 v66, 0xffff0000, v60
	v_and_b32_e32 v82, 0xffff0000, v56
	v_lshlrev_b32_e32 v94, 16, v57
	v_and_b32_e32 v98, 0xffff0000, v57
	v_lshlrev_b32_e32 v65, 16, v58
	v_lshlrev_b32_e32 v64, 16, v60
	v_pk_mul_f32 v[116:117], v[66:67], v[66:67]
	v_and_b32_e32 v57, 0xffff0000, v106
	v_and_b32_e32 v56, 0xffff0000, v108
	v_lshlrev_b32_e32 v69, 16, v59
	v_lshlrev_b32_e32 v68, 16, v61
	v_and_b32_e32 v71, 0xffff0000, v59
	v_and_b32_e32 v70, 0xffff0000, v61
	v_lshlrev_b32_e32 v73, 16, v62
	v_and_b32_e32 v81, 0xffff0000, v62
	v_lshlrev_b32_e32 v87, 16, v63
	v_and_b32_e32 v97, 0xffff0000, v63
	v_lshlrev_b32_e32 v59, 16, v106
	v_lshlrev_b32_e32 v58, 16, v108
	v_lshlrev_b32_e32 v63, 16, v107
	v_lshlrev_b32_e32 v62, 16, v109
	v_and_b32_e32 v61, 0xffff0000, v107
	v_and_b32_e32 v60, 0xffff0000, v109
	v_pk_fma_f32 v[106:107], v[64:65], v[64:65], v[116:117]
	v_pk_mul_f32 v[108:109], v[56:57], v[56:57]
	v_pk_fma_f32 v[106:107], v[68:69], v[68:69], v[106:107]
	v_pk_fma_f32 v[108:109], v[58:59], v[58:59], v[108:109]
	v_and_b32_e32 v85, 0xffff0000, v76
	v_and_b32_e32 v80, 0xffff0000, v110
	v_and_b32_e32 v84, 0xffff0000, v112
	v_pk_fma_f32 v[134:135], v[70:71], v[70:71], v[106:107]
	v_pk_fma_f32 v[106:107], v[62:63], v[62:63], v[108:109]
	v_lshlrev_b32_e32 v75, 16, v76
	v_lshlrev_b32_e32 v72, 16, v110
	v_lshlrev_b32_e32 v74, 16, v112
	v_pk_fma_f32 v[136:137], v[60:61], v[60:61], v[106:107]
	v_pk_mul_f32 v[106:107], v[80:81], v[80:81]
	v_pk_mul_f32 v[108:109], v[84:85], v[84:85]
	v_lshlrev_b32_e32 v91, 16, v77
	v_lshlrev_b32_e32 v86, 16, v111
	v_lshlrev_b32_e32 v90, 16, v113
	v_pk_fma_f32 v[106:107], v[72:73], v[72:73], v[106:107]
	v_pk_fma_f32 v[108:109], v[74:75], v[74:75], v[108:109]
	v_and_b32_e32 v103, 0xffff0000, v77
	v_and_b32_e32 v96, 0xffff0000, v111
	v_and_b32_e32 v102, 0xffff0000, v113
	v_pk_fma_f32 v[106:107], v[86:87], v[86:87], v[106:107]
	v_pk_fma_f32 v[108:109], v[90:91], v[90:91], v[108:109]
	v_and_b32_e32 v89, 0xffff0000, v104
	v_and_b32_e32 v88, 0xffff0000, v114
	v_pk_fma_f32 v[106:107], v[96:97], v[96:97], v[106:107]
	v_pk_fma_f32 v[108:109], v[102:103], v[102:103], v[108:109]
	v_lshlrev_b32_e32 v77, 16, v104
	v_lshlrev_b32_e32 v76, 16, v114
	v_pk_add_f32 v[106:107], v[106:107], v[108:109]
	v_pk_mul_f32 v[108:109], v[88:89], v[88:89]
	v_lshlrev_b32_e32 v93, 16, v105
	v_lshlrev_b32_e32 v92, 16, v115
	v_pk_fma_f32 v[108:109], v[76:77], v[76:77], v[108:109]
	v_and_b32_e32 v105, 0xffff0000, v105
	v_and_b32_e32 v104, 0xffff0000, v115
	v_pk_fma_f32 v[108:109], v[92:93], v[92:93], v[108:109]
	v_and_b32_e32 v117, 0xffff0000, v120
	v_and_b32_e32 v116, 0xffff0000, v122
	v_pk_fma_f32 v[108:109], v[104:105], v[104:105], v[108:109]
	v_lshlrev_b32_e32 v79, 16, v46
	v_lshlrev_b32_e32 v95, 16, v47
	v_and_b32_e32 v99, 0xffff0000, v47
	v_pk_mul_f32 v[46:47], v[82:83], v[82:83]
	v_lshlrev_b32_e32 v114, 16, v122
	v_lshlrev_b32_e32 v115, 16, v120
	v_pk_add_f32 v[106:107], v[106:107], v[108:109]
	v_pk_mul_f32 v[108:109], v[116:117], v[116:117]
	v_pk_fma_f32 v[46:47], v[78:79], v[78:79], v[46:47]
	v_lshlrev_b32_e32 v118, 16, v123
	v_lshlrev_b32_e32 v119, 16, v121
	v_pk_fma_f32 v[108:109], v[114:115], v[114:115], v[108:109]
	v_pk_fma_f32 v[46:47], v[94:95], v[94:95], v[46:47]
	v_and_b32_e32 v121, 0xffff0000, v121
	v_and_b32_e32 v120, 0xffff0000, v123
	v_pk_fma_f32 v[108:109], v[118:119], v[118:119], v[108:109]
	v_pk_fma_f32 v[46:47], v[98:99], v[98:99], v[46:47]
	v_pk_fma_f32 v[108:109], v[120:121], v[120:121], v[108:109]
	v_lshlrev_b32_e32 v110, 16, v131
	v_pk_add_f32 v[106:107], v[106:107], v[108:109]
	v_mov_b32_e32 v108, v136
	v_mov_b32_e32 v109, v46
	v_pk_add_f32 v[122:123], v[106:107], v[108:109]
	v_and_b32_e32 v109, 0xffff0000, v132
	v_and_b32_e32 v108, 0xffff0000, v130
	v_lshlrev_b32_e32 v107, 16, v132
	v_lshlrev_b32_e32 v106, 16, v130
	v_and_b32_e32 v112, 0xffff0000, v131
	v_pk_mul_f32 v[130:131], v[108:109], v[108:109]
	v_lshlrev_b32_e32 v111, 16, v133
	v_pk_fma_f32 v[130:131], v[106:107], v[106:107], v[130:131]
	v_and_b32_e32 v113, 0xffff0000, v133
	v_pk_fma_f32 v[130:131], v[110:111], v[110:111], v[130:131]
	v_mov_b32_e32 v46, v137
	v_pk_fma_f32 v[130:131], v[112:113], v[112:113], v[130:131]
	v_pk_add_f32 v[46:47], v[122:123], v[46:47]
	v_mov_b32_e32 v122, v130
	v_mov_b32_e32 v123, v134
	v_pk_add_f32 v[46:47], v[46:47], v[122:123]
	v_mov_b32_e32 v134, v131
	v_pk_add_f32 v[46:47], v[46:47], v[134:135]
	ds_bpermute_b32 v123, v55, v47
	ds_bpermute_b32 v122, v55, v46
	global_load_dwordx4 v[130:133], v[100:101], off offset:3072 nt
	global_load_dwordx4 v[134:137], v[178:179], off nt
	global_load_dwordx4 v[138:141], v[178:179], off offset:1024 nt
	global_load_dwordx4 v[142:145], v[178:179], off offset:2048 nt
	global_load_dwordx4 v[146:149], v[178:179], off offset:3072 nt
	global_load_dwordx4 v[150:153], v[180:181], off nt
	global_load_dwordx4 v[154:157], v[180:181], off offset:1024 nt
	global_load_dwordx4 v[158:161], v[180:181], off offset:2048 nt
	global_load_dwordx4 v[162:165], v[180:181], off offset:3072 nt
	s_waitcnt lgkmcnt(0)
	v_pk_add_f32 v[46:47], v[46:47], v[122:123]
	ds_bpermute_b32 v123, v124, v47
	ds_bpermute_b32 v122, v124, v46
	v_mov_b32_e32 v186, v73
	v_mov_b32_e32 v187, v81
	v_mov_b32_e32 v188, v87
	v_mov_b32_e32 v189, v97
	s_waitcnt lgkmcnt(0)
	v_pk_add_f32 v[46:47], v[46:47], v[122:123]
	ds_bpermute_b32 v123, v125, v47
	ds_bpermute_b32 v122, v125, v46
	v_mov_b32_e32 v73, v80
	v_mov_b32_e32 v87, v96
	s_waitcnt lgkmcnt(0)
	v_pk_add_f32 v[46:47], v[46:47], v[122:123]
	ds_bpermute_b32 v123, v126, v47
	ds_bpermute_b32 v122, v126, v46
	s_waitcnt lgkmcnt(0)
	v_pk_add_f32 v[44:45], v[46:47], v[122:123]
	ds_bpermute_b32 v47, v127, v45
	ds_bpermute_b32 v46, v127, v44
	v_add_co_u32_e32 v122, vcc, s3, v180
	s_waitcnt lgkmcnt(0)
	v_pk_add_f32 v[44:45], v[44:45], v[46:47]
	ds_bpermute_b32 v47, v128, v45
	ds_bpermute_b32 v46, v128, v44
	v_addc_co_u32_e32 v123, vcc, 0, v181, vcc
	s_waitcnt lgkmcnt(0)
	v_pk_add_f32 v[44:45], v[44:45], v[46:47]
	s_nop 0
	v_pk_fma_f32 v[182:183], v[44:45], s[2:3], v[54:55] op_sel_hi:[1,0,0]
	s_nop 0
	v_mul_f32_e32 v44, 0x4b800000, v183
	v_cmp_gt_f32_e32 vcc, s5, v183
	s_nop 1
	v_cndmask_b32_e32 v44, v183, v44, vcc
	v_rsq_f32_e32 v49, v44
	global_load_dwordx4 v[166:169], v[122:123], off nt
	global_load_dwordx4 v[170:173], v[122:123], off offset:1024 nt
	global_load_dwordx4 v[174:177], v[122:123], off offset:2048 nt
	global_load_dwordx4 v[44:47], v[122:123], off offset:3072 nt
	v_mul_f32_e32 v129, 0x45800000, v49
	v_cndmask_b32_e32 v184, v49, v129, vcc
	v_pk_mul_f32 v[186:187], v[186:187], v[184:185] op_sel_hi:[1,0]
	v_pk_mul_f32 v[188:189], v[188:189], v[184:185] op_sel_hi:[1,0]
	v_pk_fma_f32 v[40:41], v[0:1], v[186:187], v[40:41]
	v_pk_fma_f32 v[42:43], v[2:3], v[188:189], v[42:43]
	global_store_dwordx4 v[100:101], v[40:43], off nt
	v_cmp_gt_f32_e32 vcc, s5, v182
	s_nop 0
	v_mov_b32_e32 v40, v75
	v_mov_b32_e32 v41, v85
	v_mov_b32_e32 v42, v91
	v_mov_b32_e32 v43, v103
	v_pk_mul_f32 v[40:41], v[40:41], v[184:185] op_sel_hi:[1,0]
	v_pk_mul_f32 v[42:43], v[42:43], v[184:185] op_sel_hi:[1,0]
	v_pk_fma_f32 v[36:37], v[4:5], v[40:41], v[36:37]
	v_pk_fma_f32 v[38:39], v[6:7], v[42:43], v[38:39]
	global_store_dwordx4 v[100:101], v[36:39], off offset:1024 nt
	v_mov_b32_e32 v75, v84
	v_mov_b32_e32 v91, v102
	v_mov_b32_e32 v36, v77
	v_mov_b32_e32 v37, v89
	v_mov_b32_e32 v38, v93
	v_mov_b32_e32 v39, v105
	v_pk_mul_f32 v[36:37], v[36:37], v[184:185] op_sel_hi:[1,0]
	v_pk_mul_f32 v[38:39], v[38:39], v[184:185] op_sel_hi:[1,0]
	v_pk_fma_f32 v[32:33], v[8:9], v[36:37], v[32:33]
	v_pk_fma_f32 v[34:35], v[10:11], v[38:39], v[34:35]
	global_store_dwordx4 v[100:101], v[32:35], off offset:2048 nt
	v_mul_f32_e32 v36, 0x4b800000, v182
	v_cndmask_b32_e32 v36, v182, v36, vcc
	v_mov_b32_e32 v32, v115
	v_mov_b32_e32 v33, v117
	v_mov_b32_e32 v34, v119
	v_mov_b32_e32 v35, v121
	v_pk_mul_f32 v[32:33], v[32:33], v[184:185] op_sel_hi:[1,0]
	v_pk_mul_f32 v[34:35], v[34:35], v[184:185] op_sel_hi:[1,0]
	s_waitcnt vmcnt(15)
	v_pk_fma_f32 v[32:33], v[12:13], v[32:33], v[130:131]
	v_pk_fma_f32 v[34:35], v[14:15], v[34:35], v[132:133]
	global_store_dwordx4 v[100:101], v[32:35], off offset:3072 nt
	v_rsq_f32_e32 v36, v36
	v_mov_b32_e32 v77, v88
	v_mov_b32_e32 v32, v78
	v_mov_b32_e32 v33, v82
	v_mov_b32_e32 v34, v94
	v_mov_b32_e32 v35, v98
	v_pk_mul_f32 v[32:33], v[32:33], v[184:185] op_sel_hi:[1,0]
	v_pk_mul_f32 v[34:35], v[34:35], v[184:185] op_sel_hi:[1,0]
	s_waitcnt vmcnt(15)
	v_pk_fma_f32 v[32:33], v[16:17], v[32:33], v[134:135]
	v_pk_fma_f32 v[34:35], v[18:19], v[34:35], v[136:137]
	v_mov_b32_e32 v82, v79
	v_mov_b32_e32 v98, v95
	global_store_dwordx4 v[178:179], v[32:35], off nt
	v_mov_b32_e32 v93, v104
	v_mov_b32_e32 v115, v116
	v_pk_mul_f32 v[32:33], v[82:83], v[184:185] op_sel_hi:[1,0]
	v_pk_mul_f32 v[34:35], v[98:99], v[184:185] op_sel_hi:[1,0]
	s_waitcnt vmcnt(15)
	v_pk_fma_f32 v[32:33], v[20:21], v[32:33], v[138:139]
	v_pk_fma_f32 v[34:35], v[22:23], v[34:35], v[140:141]
	global_store_dwordx4 v[178:179], v[32:35], off offset:1024 nt
	v_mov_b32_e32 v119, v120
	s_nop 0
	v_mov_b32_e32 v32, v64
	v_mov_b32_e32 v33, v66
	v_mov_b32_e32 v34, v68
	v_mov_b32_e32 v35, v70
	v_pk_mul_f32 v[32:33], v[32:33], v[184:185] op_sel_hi:[1,0]
	v_pk_mul_f32 v[34:35], v[34:35], v[184:185] op_sel_hi:[1,0]
	s_waitcnt vmcnt(15)
	v_pk_fma_f32 v[32:33], v[24:25], v[32:33], v[142:143]
	v_pk_fma_f32 v[34:35], v[26:27], v[34:35], v[144:145]
	v_mov_b32_e32 v66, v65
	v_mov_b32_e32 v70, v69
	global_store_dwordx4 v[178:179], v[32:35], off offset:2048 nt
	s_nop 1
	v_pk_mul_f32 v[32:33], v[66:67], v[184:185] op_sel_hi:[1,0]
	v_pk_mul_f32 v[34:35], v[70:71], v[184:185] op_sel_hi:[1,0]
	s_waitcnt vmcnt(15)
	v_pk_fma_f32 v[32:33], v[28:29], v[32:33], v[146:147]
	v_pk_fma_f32 v[34:35], v[30:31], v[34:35], v[148:149]
	global_store_dwordx4 v[178:179], v[32:35], off offset:3072 nt
	s_nop 1
	v_mul_f32_e32 v32, 0x45800000, v36
	v_cndmask_b32_e32 v36, v36, v32, vcc
	v_pk_mul_f32 v[32:33], v[72:73], v[36:37] op_sel_hi:[1,0]
	v_pk_mul_f32 v[34:35], v[86:87], v[36:37] op_sel_hi:[1,0]
	s_waitcnt vmcnt(15)
	v_pk_fma_f32 v[32:33], v[0:1], v[32:33], v[150:151]
	v_pk_fma_f32 v[34:35], v[2:3], v[34:35], v[152:153]
	global_store_dwordx4 v[180:181], v[32:35], off nt
	v_cmp_lt_i32_e32 vcc, s6, v48
	s_or_b64 s[0:1], vcc, s[0:1]
	v_pk_mul_f32 v[32:33], v[74:75], v[36:37] op_sel_hi:[1,0]
	v_pk_mul_f32 v[34:35], v[90:91], v[36:37] op_sel_hi:[1,0]
	s_waitcnt vmcnt(15)
	v_pk_fma_f32 v[32:33], v[4:5], v[32:33], v[154:155]
	v_pk_fma_f32 v[34:35], v[6:7], v[34:35], v[156:157]
	global_store_dwordx4 v[180:181], v[32:35], off offset:1024 nt
	s_nop 1
	v_pk_mul_f32 v[32:33], v[76:77], v[36:37] op_sel_hi:[1,0]
	v_pk_mul_f32 v[34:35], v[92:93], v[36:37] op_sel_hi:[1,0]
	s_waitcnt vmcnt(15)
	v_pk_fma_f32 v[32:33], v[8:9], v[32:33], v[158:159]
	v_pk_fma_f32 v[34:35], v[10:11], v[34:35], v[160:161]
	global_store_dwordx4 v[180:181], v[32:35], off offset:2048 nt
	s_nop 1
	v_pk_mul_f32 v[32:33], v[114:115], v[36:37] op_sel_hi:[1,0]
	v_pk_mul_f32 v[34:35], v[118:119], v[36:37] op_sel_hi:[1,0]
	s_waitcnt vmcnt(15)
	v_pk_fma_f32 v[32:33], v[12:13], v[32:33], v[162:163]
	v_pk_fma_f32 v[34:35], v[14:15], v[34:35], v[164:165]
	global_store_dwordx4 v[180:181], v[32:35], off offset:3072 nt
	s_nop 1
	v_mov_b32_e32 v32, v58
	v_mov_b32_e32 v33, v56
	v_mov_b32_e32 v34, v62
	v_mov_b32_e32 v35, v60
	v_pk_mul_f32 v[32:33], v[32:33], v[36:37] op_sel_hi:[1,0]
	v_pk_mul_f32 v[34:35], v[34:35], v[36:37] op_sel_hi:[1,0]
	s_waitcnt vmcnt(15)
	v_pk_fma_f32 v[32:33], v[16:17], v[32:33], v[166:167]
	v_pk_fma_f32 v[34:35], v[18:19], v[34:35], v[168:169]
	v_mov_b32_e32 v56, v59
	v_mov_b32_e32 v60, v63
	global_store_dwordx4 v[122:123], v[32:35], off nt
	s_nop 1
	v_pk_mul_f32 v[32:33], v[56:57], v[36:37] op_sel_hi:[1,0]
	v_pk_mul_f32 v[34:35], v[60:61], v[36:37] op_sel_hi:[1,0]
	s_waitcnt vmcnt(15)
	v_pk_fma_f32 v[32:33], v[20:21], v[32:33], v[170:171]
	v_pk_fma_f32 v[34:35], v[22:23], v[34:35], v[172:173]
	global_store_dwordx4 v[122:123], v[32:35], off offset:1024 nt
	s_nop 1
	v_mov_b32_e32 v32, v106
	v_mov_b32_e32 v33, v108
	v_mov_b32_e32 v34, v110
	v_mov_b32_e32 v35, v112
	v_pk_mul_f32 v[32:33], v[32:33], v[36:37] op_sel_hi:[1,0]
	v_pk_mul_f32 v[34:35], v[34:35], v[36:37] op_sel_hi:[1,0]
	s_waitcnt vmcnt(15)
	v_pk_fma_f32 v[32:33], v[24:25], v[32:33], v[174:175]
	v_pk_fma_f32 v[34:35], v[26:27], v[34:35], v[176:177]
	v_mov_b32_e32 v108, v107
	v_mov_b32_e32 v112, v111
	global_store_dwordx4 v[122:123], v[32:35], off offset:2048 nt
	s_nop 1
	v_pk_mul_f32 v[32:33], v[108:109], v[36:37] op_sel_hi:[1,0]
	v_pk_mul_f32 v[34:35], v[112:113], v[36:37] op_sel_hi:[1,0]
	s_waitcnt vmcnt(15)
	v_pk_fma_f32 v[32:33], v[28:29], v[32:33], v[44:45]
	v_pk_fma_f32 v[34:35], v[30:31], v[34:35], v[46:47]
	global_store_dwordx4 v[122:123], v[32:35], off offset:3072 nt
	s_andn2_b64 exec, exec, s[0:1]
	s_cbranch_execnz .LBB0_1491
